# gemm_z K loop: SADDR-form tile loads (scalar tile+k base, constant per-thread row offsets) replacing 16 64-bit VALU adds per trip
# speedup vs baseline: 1.0049x; 1.0049x over previous
; #define GL_LOAD(KT_, S) { int kt_ = MID ? (((KT_) & 8) | (((KT_) + rot) & 7)) : (((KT_) + rot) & (KT - 1)); kt_ &= ktmask; asm volatile("" : "+s"(kt_)); GL_LD1(0, S) GL_LD1(1, S) GL_LD1(2, S) GL_LD1(3, S) }
; #define GL_STORE(BUF_, S, DOSSQ_) { const bool dossq_ = (DOSSQ_); GL_ST1(0, S, BUF_, ssq0) GL_ST1(1, S, BUF_, ssq1) GL_ST1(2, S, BUF_, ssq2) GL_ST1(3, S, BUF_, ssq3) }
;     ...
;   __syncthreads();
;   GL_LOAD(0, 0);
;   GL_LOAD(1, 1);
;   GL_STORE(0, 0, true);
;   __syncthreads();
; __device__ void phase_gemm_z(const P& p, int vb, int nvb, char* smem) {
;     ...
;   for (int li = xs ? slot : vb; li < (xs ? 33 * 12 : 264 * 12); li += (xs ? nslot : nvb)) {
;     const int mt = xs ? (li / 12) * 8 + xcd : li / 12, nt = li % 12;
;     const char* arow[4]; const bool az[4] = {false, false, false, false};
; #pragma unroll
;     for (int i = 0; i < 4; i++) arow[i] = p.ws + WS_HB + (size_t)(mt * 128 + r0 + 32 * i) * 2048;
;     gemm_core<0, false, false, 1024>(smem, arow, az, (const uint16_t*)(p.ws + WS_WT_IN), nt * 128, (nt * 4) / 3);
.LBB0_62:
	s_mul_hi_i32 s0, s38, 0x2aaaaaab
	s_lshr_b32 s1, s0, 31
	s_ashr_i32 s0, s0, 1
	s_add_i32 s12, s0, s1
	s_lshl_b32 s0, s12, 3
	s_or_b32 s13, s0, s33
	s_and_b64 s[0:1], s[54:55], exec
	s_cselect_b32 s0, s13, s12
	s_mul_i32 s12, s12, 12
	s_sub_i32 s13, s38, s12
	s_lshl_b32 s39, s0, 7
	s_lshl_b32 s0, s13, 2
	s_bfe_i32 s0, s0, 0x80000
	v_mov_b32_e32 v36, v178
	s_lshl_b32 s12, s13, 7
	s_mulk_i32 s0, 0x56
	s_bfe_u32 s1, s0, 0x1000f
	v_ashrrev_i32_e32 v209, 3, v36
	s_bfe_u32 s0, s0, 0x80008
	v_add_u32_e32 v2, s12, v209
	v_add_u32_e32 v0, s39, v180
	s_add_i32 s0, s0, s1
	v_ashrrev_i32_e32 v3, 31, v2
	v_and_b32_e32 v208, 7, v36
	v_lshlrev_b64 v[2:3], 11, v[2:3]
	s_and_b32 s14, s0, 15
	v_ashrrev_i32_e32 v1, 31, v0
	v_lshl_add_u64 v[2:3], s[80:81], 0, v[2:3]
	v_lshlrev_b32_e32 v156, 4, v208
	s_barrier
	s_lshl_b32 s16, s14, 6
	v_lshlrev_b64 v[0:1], 11, v[0:1]
	s_ashr_i32 s15, s14, 31
	v_lshl_add_u64 v[162:163], v[2:3], 0, v[156:157]
	s_ashr_i32 s17, s16, 31
	v_lshl_add_u64 v[164:165], s[52:53], 0, v[0:1]
	s_lshl_b64 s[14:15], s[14:15], 7
	s_lshl_b64 s[16:17], s[16:17], 1
	v_or_b32_e32 v8, s14, v156
	v_mov_b32_e32 v9, s15
	v_lshl_add_u64 v[166:167], v[164:165], 0, s[6:7]
	v_lshl_add_u64 v[168:169], v[164:165], 0, s[8:9]
	v_lshl_add_u64 v[170:171], v[164:165], 0, s[10:11]
	v_lshl_add_u64 v[172:173], v[162:163], 0, s[6:7]
	v_lshl_add_u64 v[2:3], v[162:163], 0, s[16:17]
	v_lshl_add_u64 v[4:5], v[164:165], 0, v[8:9]
	v_lshl_add_u64 v[10:11], v[166:167], 0, v[8:9]
	v_lshl_add_u64 v[12:13], v[168:169], 0, v[8:9]
	v_lshl_add_u64 v[16:17], v[170:171], 0, v[8:9]
	v_lshl_add_u64 v[20:21], v[172:173], 0, s[16:17]
	v_lshl_add_u64 v[174:175], v[162:163], 0, s[8:9]
	global_load_dwordx4 v[0:3], v[2:3], off
	s_nop 0
	global_load_dwordx4 v[4:7], v[4:5], off
	s_nop 0
	global_load_dwordx4 v[8:11], v[10:11], off
	s_nop 0
	global_load_dwordx4 v[12:15], v[12:13], off
	s_nop 0
	global_load_dwordx4 v[16:19], v[16:17], off
	v_lshl_add_u64 v[24:25], v[174:175], 0, s[16:17]
	global_load_dwordx4 v[20:23], v[20:21], off
	v_lshl_add_u64 v[176:177], v[162:163], 0, s[10:11]
	global_load_dwordx4 v[24:27], v[24:25], off
	v_lshl_add_u64 v[28:29], v[176:177], 0, s[16:17]
	global_load_dwordx4 v[28:31], v[28:29], off
	s_add_i32 s1, s0, 1
	s_and_b32 s16, s1, 15
	s_ashr_i32 s17, s16, 31
	s_lshl_b32 s40, s16, 6
	v_mul_lo_u32 v32, v209, s20
	s_lshl_b64 s[16:17], s[16:17], 7
	s_ashr_i32 s41, s40, 31
	v_add3_u32 v213, 16, v32, v156
	v_or_b32_e32 v32, s16, v156
	v_mov_b32_e32 v33, s17
	s_lshl_b64 s[16:17], s[40:41], 1
	v_lshl_add_u64 v[34:35], v[164:165], 0, v[32:33]
	s_and_b32 s14, s0, 0xff
	s_add_i32 s0, s0, 2
	s_and_b32 s0, s0, 15
	v_mov_b32_e32 v214, v157
	v_mov_b32_e32 v215, v157
	v_mov_b32_e32 v216, v157
	v_mov_b32_e32 v217, v157
	v_bfe_u32 v210, v36, 6, 1
	v_and_b32_e32 v211, 31, v36
	v_bfe_u32 v212, v36, 5, 1
	v_mov_b32_e32 v37, v157
	v_mov_b32_e32 v38, v157
	v_mov_b32_e32 v39, v157
	v_mov_b32_e32 v40, v157
	v_mov_b32_e32 v41, v157
	v_mov_b32_e32 v42, v157
	v_mov_b32_e32 v43, v157
	v_mov_b32_e32 v44, v157
	v_mov_b32_e32 v45, v157
	v_mov_b32_e32 v46, v157
	v_mov_b32_e32 v47, v157
	v_mov_b32_e32 v48, v157
	v_mov_b32_e32 v49, v157
	v_mov_b32_e32 v50, v157
	v_mov_b32_e32 v51, v157
	v_mov_b32_e32 v52, v157
	v_mov_b32_e32 v53, v157
	v_mov_b32_e32 v54, v157
	v_mov_b32_e32 v55, v157
	v_mov_b32_e32 v56, v157
	v_mov_b32_e32 v57, v157
	v_mov_b32_e32 v58, v157
	v_mov_b32_e32 v59, v157
	v_mov_b32_e32 v60, v157
	v_mov_b32_e32 v61, v157
	v_mov_b32_e32 v62, v157
	v_mov_b32_e32 v63, v157
	v_add_u32_e32 v221, 0x1200, v213
	v_add_u32_e32 v222, 0x2400, v213
	v_add_u32_e32 v223, 0x3600, v213
	s_waitcnt vmcnt(7)
	ds_write_b128 v213, v[0:3] offset:36864
	s_waitcnt vmcnt(6)
	ds_write_b128 v213, v[4:7]
	s_waitcnt vmcnt(5)
	ds_write_b128 v213, v[8:11] offset:4608
	v_lshl_add_u64 v[0:1], v[162:163], 0, s[16:17]
	s_waitcnt vmcnt(2)
	ds_write_b128 v213, v[20:23] offset:41472
	global_load_dwordx4 v[80:83], v[34:35], off
	global_load_dwordx4 v[72:75], v[0:1], off
	v_lshl_add_u64 v[0:1], v[166:167], 0, v[32:33]
	ds_write_b128 v213, v[12:15] offset:9216
	s_waitcnt vmcnt(3)
	ds_write_b128 v213, v[24:27] offset:46080
	v_lshl_add_u64 v[2:3], v[172:173], 0, s[16:17]
	global_load_dwordx4 v[84:87], v[0:1], off
	global_load_dwordx4 v[64:67], v[2:3], off
	v_lshl_add_u64 v[0:1], v[168:169], 0, v[32:33]
	ds_write_b128 v213, v[16:19] offset:13824
	s_waitcnt vmcnt(4)
	ds_write_b128 v213, v[28:31] offset:50688
	v_lshl_add_u64 v[2:3], v[174:175], 0, s[16:17]
	global_load_dwordx4 v[88:91], v[0:1], off
	global_load_dwordx4 v[68:71], v[2:3], off
	v_lshl_add_u64 v[0:1], v[170:171], 0, v[32:33]
	v_lshl_add_u64 v[2:3], v[176:177], 0, s[16:17]
	global_load_dwordx4 v[108:111], v[0:1], off
	global_load_dwordx4 v[76:79], v[2:3], off
	s_waitcnt lgkmcnt(0)
	s_barrier
; #define GL_LOAD(KT_, S) { int kt_ = MID ? (((KT_) & 8) | (((KT_) + rot) & 7)) : (((KT_) + rot) & (KT - 1)); kt_ &= ktmask; asm volatile("" : "+s"(kt_)); GL_LD1(0, S) GL_LD1(1, S) GL_LD1(2, S) GL_LD1(3, S) }
; #define GL_STORE(BUF_, S, DOSSQ_) { const bool dossq_ = (DOSSQ_); GL_ST1(0, S, BUF_, ssq0) GL_ST1(1, S, BUF_, ssq1) GL_ST1(2, S, BUF_, ssq2) GL_ST1(3, S, BUF_, ssq3) }
; #define GL_RS(DEN_) { GL_RS1(0, ssq0, DEN_) GL_RS1(1, ssq1, DEN_) GL_RS1(2, ssq2, DEN_) GL_RS1(3, ssq3, DEN_) }
;     ...
;   const uint16_t* brow = Bt + (size_t)(n0 + r0 * bm) * K + kc * 8;
;     ...
;     GL_LOAD(2, 0);
; #pragma unroll 1
;     for (int kt = 0; kt < KT; kt += 2) {
;       if (MID && kt == 8) {
;         GL_RS(512.f);
;         __syncthreads();
; #pragma unroll
;         for (int mi = 0; mi < 2; mi++) {
;           f32x16 sv;
; #pragma unroll
;           for (int r = 0; r < 16; r++) sv[r] = rs[64 * wm + 32 * mi + (r & 3) + 8 * (r >> 2) + 4 * lh];
;           acc[mi][0] *= sv; acc[mi][1] *= sv;
;         }
;       }
;       GL_COMPUTE(0);
;       GL_STORE(1, 1, !MID || (kt + 1) < 8);
;       GL_LOAD((kt + 3 < KT ? kt + 3 : KT - 1), 1);
;       __syncthreads();
;       GL_COMPUTE(1);
;       GL_STORE(0, 0, (kt + 2 < KT) && (!MID || (kt + 2) < 8));
;       GL_LOAD((kt + 4 < KT ? kt + 4 : KT - 1), 0);
;       __syncthreads();
;     }
	s_ashr_i32 s1, s0, 31
	s_lshl_b64 s[16:17], s[0:1], 7
	s_lshl_b32 s0, s0, 6
	v_dot2c_f32_bf16_e32 v214, v4, v4
	v_or_b32_e32 v0, s16, v156
	v_mov_b32_e32 v1, s17
	s_ashr_i32 s1, s0, 31
	v_dot2c_f32_bf16_e32 v215, v8, v8
	v_dot2c_f32_bf16_e32 v214, v5, v5
	s_lshl_b64 s[0:1], s[0:1], 1
	v_lshl_add_u64 v[2:3], v[164:165], 0, v[0:1]
	v_dot2c_f32_bf16_e32 v215, v9, v9
	v_dot2c_f32_bf16_e32 v214, v6, v6
	v_lshl_add_u64 v[4:5], v[166:167], 0, v[0:1]
	v_lshl_add_u64 v[8:9], v[162:163], 0, s[0:1]
	global_load_dwordx4 v[92:95], v[2:3], off
	global_load_dwordx4 v[124:127], v[8:9], off
	v_lshl_add_u64 v[2:3], v[172:173], 0, s[0:1]
	v_dot2c_f32_bf16_e32 v214, v7, v7
	v_lshl_add_u64 v[6:7], v[168:169], 0, v[0:1]
	v_lshl_add_u64 v[0:1], v[170:171], 0, v[0:1]
	global_load_dwordx4 v[96:99], v[4:5], off
	global_load_dwordx4 v[120:123], v[2:3], off
	v_lshl_add_u64 v[2:3], v[174:175], 0, s[0:1]
	global_load_dwordx4 v[100:103], v[6:7], off
	global_load_dwordx4 v[116:119], v[2:3], off
	v_lshl_add_u64 v[2:3], v[176:177], 0, s[0:1]
	global_load_dwordx4 v[104:107], v[0:1], off
	global_load_dwordx4 v[112:115], v[2:3], off
	v_ashrrev_i32_e32 v0, 1, v36
	v_dot2c_f32_bf16_e32 v216, v12, v12
	v_dot2c_f32_bf16_e32 v217, v16, v16
	v_and_b32_e32 v218, 0xffffffc0, v0
	v_dot2c_f32_bf16_e32 v216, v13, v13
	v_dot2c_f32_bf16_e32 v217, v17, v17
	v_or_b32_e32 v0, v218, v211
	v_lshl_or_b32 v2, v210, 6, v211
	v_dot2c_f32_bf16_e32 v215, v10, v10
	v_dot2c_f32_bf16_e32 v216, v14, v14
	v_dot2c_f32_bf16_e32 v217, v18, v18
	v_lshl_add_u32 v1, v212, 4, 16
	v_mul_lo_u32 v0, v0, s20
	v_mul_u32_u24_e32 v2, 0x90, v2
	v_dot2c_f32_bf16_e32 v215, v11, v11
	v_dot2c_f32_bf16_e32 v216, v15, v15
	v_dot2c_f32_bf16_e32 v217, v19, v19
	v_add_u32_e32 v219, v1, v0
	v_add_u32_e32 v220, v1, v2
	s_add_i32 s0, s14, 3
	s_add_i32 s1, s14, 4
	s_mov_b32 s14, 0
	v_mov_b32_e32 v0, v157
	v_mov_b32_e32 v1, v157
	v_mov_b32_e32 v2, v157
	v_mov_b32_e32 v3, v157
	v_mov_b32_e32 v4, v157
	v_mov_b32_e32 v5, v157
	v_mov_b32_e32 v6, v157
	v_mov_b32_e32 v7, v157
	v_mov_b32_e32 v8, v157
	v_mov_b32_e32 v9, v157
	v_mov_b32_e32 v10, v157
	v_mov_b32_e32 v11, v157
	v_mov_b32_e32 v12, v157
	v_mov_b32_e32 v13, v157
	v_mov_b32_e32 v14, v157
	v_mov_b32_e32 v15, v157
	v_mov_b32_e32 v16, v157
	v_mov_b32_e32 v17, v157
	v_mov_b32_e32 v18, v157
	v_mov_b32_e32 v19, v157
	v_mov_b32_e32 v20, v157
	v_mov_b32_e32 v21, v157
	v_mov_b32_e32 v22, v157
	v_mov_b32_e32 v23, v157
	v_mov_b32_e32 v24, v157
	v_mov_b32_e32 v25, v157
	v_mov_b32_e32 v26, v157
	v_mov_b32_e32 v27, v157
	v_mov_b32_e32 v28, v157
	v_mov_b32_e32 v29, v157
	v_mov_b32_e32 v30, v157
	v_mov_b32_e32 v31, v157
	v_mov_b32_e32 v32, v157
	v_mov_b32_e32 v33, v157
	v_mov_b32_e32 v34, v157
	v_mov_b32_e32 v35, v157
	v_mov_b32_e32 v36, v157
	v_lshl_or_b32 v250, v209, 11, v156
	v_add_u32_e32 v251, 0x10000, v250
	v_add_u32_e32 v252, 0x20000, v250
	v_add_u32_e32 v253, 0x30000, v250
	s_lshl_b32 s98, s39, 11
	s_add_u32 s98, s52, s98
	s_addc_u32 s99, s53, 0
	s_lshl_b32 s100, s12, 11
	s_add_u32 s100, s80, s100
	s_addc_u32 s101, s81, 0
.LBB0_63:
	ds_read_b128 v[128:131], v219
	ds_read_b128 v[132:135], v220 offset:36864
	ds_read_b128 v[136:139], v220 offset:36896
	ds_read_b128 v[140:143], v219 offset:32
	ds_read_b128 v[144:147], v220 offset:41472
	ds_read_b128 v[148:151], v220 offset:41504
	s_waitcnt lgkmcnt(4)
	v_mfma_f32_32x32x16_bf16 v[48:63], v[128:131], v[132:135], v[48:63]
	s_waitcnt lgkmcnt(1)
	v_mfma_f32_32x32x16_bf16 v[32:47], v[128:131], v[144:147], v[32:47]
	ds_read_b128 v[128:131], v219 offset:4608
	ds_read_b128 v[152:155], v219 offset:4640
	s_waitcnt lgkmcnt(1)
	v_mfma_f32_32x32x16_bf16 v[16:31], v[128:131], v[132:135], v[16:31]
	v_mfma_f32_32x32x16_bf16 v[0:15], v[128:131], v[144:147], v[0:15]
	v_mfma_f32_32x32x16_bf16 v[48:63], v[140:143], v[136:139], v[48:63]
	v_mfma_f32_32x32x16_bf16 v[32:47], v[140:143], v[148:151], v[32:47]
	s_waitcnt lgkmcnt(0)
	v_mfma_f32_32x32x16_bf16 v[16:31], v[152:155], v[136:139], v[16:31]
	v_mfma_f32_32x32x16_bf16 v[0:15], v[152:155], v[148:151], v[0:15]
	ds_read_b128 v[128:131], v219 offset:64
	ds_read_b128 v[132:135], v220 offset:36928
	ds_read_b128 v[136:139], v220 offset:36960
	ds_read_b128 v[140:143], v219 offset:96
	ds_read_b128 v[144:147], v220 offset:41536
	ds_read_b128 v[148:151], v220 offset:41568
	s_min_u32 s15, s14, 12
	s_waitcnt lgkmcnt(4)
	v_mfma_f32_32x32x16_bf16 v[48:63], v[128:131], v[132:135], v[48:63]
	s_add_i32 s15, s0, s15
	s_and_b32 s16, s15, 15
	s_waitcnt vmcnt(15)
	v_dot2c_f32_bf16_e32 v214, v80, v80
	s_waitcnt vmcnt(13)
	v_dot2c_f32_bf16_e32 v215, v84, v84
	s_waitcnt vmcnt(11)
	v_dot2c_f32_bf16_e32 v216, v88, v88
	s_waitcnt vmcnt(9)
	v_dot2c_f32_bf16_e32 v217, v108, v108
	v_dot2c_f32_bf16_e32 v214, v81, v81
	s_waitcnt lgkmcnt(1)
	v_mfma_f32_32x32x16_bf16 v[32:47], v[128:131], v[144:147], v[32:47]
	ds_read_b128 v[128:131], v219 offset:4672
	ds_read_b128 v[152:155], v219 offset:4704
	ds_write_b128 v213, v[80:83] offset:18432
	ds_write_b128 v213, v[72:75] offset:55296
	ds_write_b128 v221, v[84:87] offset:18432
	ds_write_b128 v221, v[64:67] offset:55296
	ds_write_b128 v222, v[88:91] offset:18432
	ds_write_b128 v222, v[68:71] offset:55296
	ds_write_b128 v223, v[108:111] offset:18432
	s_waitcnt vmcnt(8)
	ds_write_b128 v223, v[76:79] offset:55296
	s_lshl_b32 s16, s16, 7
	s_add_u32 s40, s98, s16
	s_addc_u32 s41, s99, 0
	s_add_u32 s16, s100, s16
	s_addc_u32 s17, s101, 0
	s_waitcnt lgkmcnt(9)
	v_mfma_f32_32x32x16_bf16 v[16:31], v[128:131], v[132:135], v[16:31]
	v_mfma_f32_32x32x16_bf16 v[48:63], v[140:143], v[136:139], v[48:63]
	v_dot2c_f32_bf16_e32 v215, v85, v85
	v_dot2c_f32_bf16_e32 v216, v89, v89
	v_dot2c_f32_bf16_e32 v217, v109, v109
	v_dot2c_f32_bf16_e32 v214, v82, v82
	v_dot2c_f32_bf16_e32 v215, v86, v86
	v_mfma_f32_32x32x16_bf16 v[32:47], v[140:143], v[148:151], v[32:47]
	v_dot2c_f32_bf16_e32 v216, v90, v90
	v_dot2c_f32_bf16_e32 v217, v110, v110
	v_mfma_f32_32x32x16_bf16 v[0:15], v[128:131], v[144:147], v[0:15]
	global_load_dwordx4 v[128:131], v250, s[40:41]
	global_load_dwordx4 v[72:75], v250, s[16:17]
	global_load_dwordx4 v[132:135], v251, s[40:41]
	s_nop 0
	global_load_dwordx4 v[64:67], v251, s[16:17]
	s_waitcnt lgkmcnt(8)
	v_mfma_f32_32x32x16_bf16 v[16:31], v[152:155], v[136:139], v[16:31]
	global_load_dwordx4 v[136:139], v252, s[40:41]
	global_load_dwordx4 v[68:71], v252, s[16:17]
	s_nop 0
	global_load_dwordx4 v[140:143], v253, s[40:41]
	s_nop 0
	global_load_dwordx4 v[76:79], v253, s[16:17]
	s_waitcnt lgkmcnt(0)
	s_barrier
; #define GL_LOAD(KT_, S) { int kt_ = MID ? (((KT_) & 8) | (((KT_) + rot) & 7)) : (((KT_) + rot) & (KT - 1)); kt_ &= ktmask; asm volatile("" : "+s"(kt_)); GL_LD1(0, S) GL_LD1(1, S) GL_LD1(2, S) GL_LD1(3, S) }
; #define GL_STORE(BUF_, S, DOSSQ_) { const bool dossq_ = (DOSSQ_); GL_ST1(0, S, BUF_, ssq0) GL_ST1(1, S, BUF_, ssq1) GL_ST1(2, S, BUF_, ssq2) GL_ST1(3, S, BUF_, ssq3) }
; #define GL_RS(DEN_) { GL_RS1(0, ssq0, DEN_) GL_RS1(1, ssq1, DEN_) GL_RS1(2, ssq2, DEN_) GL_RS1(3, ssq3, DEN_) }
;     ...
;   const uint16_t* brow = Bt + (size_t)(n0 + r0 * bm) * K + kc * 8;
;     ...
;     GL_LOAD(2, 0);
; #pragma unroll 1
;     for (int kt = 0; kt < KT; kt += 2) {
;       if (MID && kt == 8) {
;         GL_RS(512.f);
;         __syncthreads();
; #pragma unroll
;         for (int mi = 0; mi < 2; mi++) {
;           f32x16 sv;
; #pragma unroll
;           for (int r = 0; r < 16; r++) sv[r] = rs[64 * wm + 32 * mi + (r & 3) + 8 * (r >> 2) + 4 * lh];
;           acc[mi][0] *= sv; acc[mi][1] *= sv;
;         }
;       }
;       GL_COMPUTE(0);
;       GL_STORE(1, 1, !MID || (kt + 1) < 8);
;       GL_LOAD((kt + 3 < KT ? kt + 3 : KT - 1), 1);
;       __syncthreads();
;       GL_COMPUTE(1);
;       GL_STORE(0, 0, (kt + 2 < KT) && (!MID || (kt + 2) < 8));
;       GL_LOAD((kt + 4 < KT ? kt + 4 : KT - 1), 0);
;       __syncthreads();
;     }
	v_mfma_f32_32x32x16_bf16 v[0:15], v[152:155], v[148:151], v[0:15]
	ds_read_b128 v[144:147], v219 offset:18432
	ds_read_b128 v[148:151], v220 offset:55296
	ds_read_b128 v[152:155], v220 offset:55328
	ds_read_b128 v[224:227], v219 offset:18464
	ds_read_b128 v[228:231], v220 offset:59904
	ds_read_b128 v[232:235], v220 offset:59936
	s_waitcnt lgkmcnt(4)
	v_mfma_f32_32x32x16_bf16 v[48:63], v[144:147], v[148:151], v[48:63]
	s_waitcnt lgkmcnt(1)
	v_mfma_f32_32x32x16_bf16 v[32:47], v[144:147], v[228:231], v[32:47]
	ds_read_b128 v[144:147], v219 offset:23040
	ds_read_b128 v[236:239], v219 offset:23072
	s_waitcnt lgkmcnt(1)
	v_mfma_f32_32x32x16_bf16 v[16:31], v[144:147], v[148:151], v[16:31]
	v_mfma_f32_32x32x16_bf16 v[0:15], v[144:147], v[228:231], v[0:15]
	v_mfma_f32_32x32x16_bf16 v[48:63], v[224:227], v[152:155], v[48:63]
	v_mfma_f32_32x32x16_bf16 v[32:47], v[224:227], v[232:235], v[32:47]
	s_waitcnt lgkmcnt(0)
	v_mfma_f32_32x32x16_bf16 v[16:31], v[236:239], v[152:155], v[16:31]
	v_mfma_f32_32x32x16_bf16 v[0:15], v[236:239], v[232:235], v[0:15]
	s_min_u32 s15, s14, 11
	v_mov_b32_e32 v227, v214
	v_mov_b32_e32 v226, v215
	v_mov_b32_e32 v225, v216
	v_mov_b32_e32 v224, v217
	s_add_i32 s15, s1, s15
	v_dot2c_f32_bf16_e32 v227, v83, v83
	v_dot2c_f32_bf16_e32 v226, v87, v87
	v_dot2c_f32_bf16_e32 v225, v91, v91
	v_dot2c_f32_bf16_e32 v224, v111, v111
	s_and_b32 s16, s15, 15
	ds_read_b128 v[228:231], v220 offset:55360
	ds_read_b128 v[144:147], v220 offset:55392
	ds_read_b128 v[232:235], v219 offset:18496
	ds_read_b128 v[236:239], v219 offset:18528
	ds_read_b128 v[240:243], v220 offset:59968
	ds_read_b128 v[148:151], v220 offset:60000
	ds_read_b128 v[244:247], v219 offset:23104
	ds_read_b128 v[152:155], v219 offset:23136
	s_waitcnt vmcnt(15)
	ds_write_b128 v213, v[92:95]
	s_waitcnt vmcnt(14)
	ds_write_b128 v213, v[124:127] offset:36864
	s_waitcnt vmcnt(13)
	ds_write_b128 v221, v[96:99]
	s_waitcnt vmcnt(12)
	ds_write_b128 v221, v[120:123] offset:36864
	s_waitcnt vmcnt(11)
	ds_write_b128 v222, v[100:103]
	s_waitcnt vmcnt(10)
	ds_write_b128 v222, v[116:119] offset:36864
	s_waitcnt vmcnt(9)
	ds_write_b128 v223, v[104:107]
	s_waitcnt vmcnt(8)
	ds_write_b128 v223, v[112:115] offset:36864
	v_mov_b32_e32 v214, v227
	v_mov_b32_e32 v215, v226
	v_mov_b32_e32 v216, v225
	v_mov_b32_e32 v217, v224
	s_lshl_b32 s16, s16, 7
	s_add_u32 s40, s98, s16
	s_addc_u32 s41, s99, 0
	s_add_u32 s16, s100, s16
	s_addc_u32 s17, s101, 0
	v_dot2c_f32_bf16_e32 v214, v92, v92
	v_dot2c_f32_bf16_e32 v215, v96, v96
	v_dot2c_f32_bf16_e32 v216, v100, v100
	v_dot2c_f32_bf16_e32 v217, v104, v104
	v_dot2c_f32_bf16_e32 v214, v93, v93
	v_dot2c_f32_bf16_e32 v215, v97, v97
	v_dot2c_f32_bf16_e32 v216, v101, v101
	v_dot2c_f32_bf16_e32 v217, v105, v105
	v_dot2c_f32_bf16_e32 v214, v94, v94
	v_dot2c_f32_bf16_e32 v215, v98, v98
	v_dot2c_f32_bf16_e32 v216, v102, v102
	v_dot2c_f32_bf16_e32 v217, v106, v106
	v_dot2c_f32_bf16_e32 v214, v95, v95
	v_dot2c_f32_bf16_e32 v215, v99, v99
	v_dot2c_f32_bf16_e32 v216, v103, v103
	v_dot2c_f32_bf16_e32 v217, v107, v107
	global_load_dwordx4 v[92:95], v250, s[40:41]
	global_load_dwordx4 v[124:127], v250, s[16:17]
	global_load_dwordx4 v[96:99], v251, s[40:41]
	global_load_dwordx4 v[120:123], v251, s[16:17]
	global_load_dwordx4 v[100:103], v252, s[40:41]
	global_load_dwordx4 v[116:119], v252, s[16:17]
	s_nop 0
	global_load_dwordx4 v[104:107], v253, s[40:41]
	global_load_dwordx4 v[112:115], v253, s[16:17]
	s_waitcnt lgkmcnt(13)
	v_mfma_f32_32x32x16_bf16 v[48:63], v[232:235], v[228:231], v[48:63]
	s_add_i32 s15, s14, 2
	s_waitcnt vmcnt(15)
	v_mov_b32_e32 v82, v130
	v_mov_b32_e32 v81, v129
	v_mov_b32_e32 v80, v128
	s_waitcnt vmcnt(13)
	v_mov_b32_e32 v86, v134
	v_mov_b32_e32 v85, v133
	v_mov_b32_e32 v84, v132
	s_waitcnt lgkmcnt(11)
	v_mfma_f32_32x32x16_bf16 v[32:47], v[232:235], v[240:243], v[32:47]
	s_waitcnt vmcnt(11)
	v_mov_b32_e32 v90, v138
	v_mov_b32_e32 v89, v137
	v_mov_b32_e32 v88, v136
	s_waitcnt vmcnt(9)
	v_mov_b32_e32 v110, v142
	v_mov_b32_e32 v109, v141
	v_mov_b32_e32 v108, v140
	v_mov_b32_e32 v83, v131
	s_waitcnt lgkmcnt(9)
	v_mfma_f32_32x32x16_bf16 v[16:31], v[244:247], v[228:231], v[16:31]
	v_mov_b32_e32 v87, v135
	v_mov_b32_e32 v91, v139
	v_mov_b32_e32 v111, v143
	s_cmp_lt_u32 s14, 14
	s_mov_b32 s14, s15
	s_waitcnt lgkmcnt(0)
	s_barrier
	v_mfma_f32_32x32x16_bf16 v[0:15], v[244:247], v[240:243], v[0:15]
	v_mfma_f32_32x32x16_bf16 v[48:63], v[236:239], v[144:147], v[48:63]
	v_mfma_f32_32x32x16_bf16 v[32:47], v[236:239], v[148:151], v[32:47]
	v_mfma_f32_32x32x16_bf16 v[16:31], v[152:155], v[144:147], v[16:31]
	v_mfma_f32_32x32x16_bf16 v[0:15], v[152:155], v[148:151], v[0:15]
	s_cbranch_scc1 .LBB0_63
	v_and_b32_e32 v65, 64, v206
	v_xor_b32_e32 v64, 1, v206
	v_add_u32_e32 v67, 64, v65
	v_cmp_lt_i32_e32 vcc, v64, v67
	v_xor_b32_e32 v66, 2, v206
	v_xor_b32_e32 v69, 4, v206
	v_cndmask_b32_e32 v64, v206, v64, vcc
	v_lshlrev_b32_e32 v65, 2, v64
	ds_bpermute_b32 v64, v65, v227
	v_cmp_lt_i32_e32 vcc, v66, v67
	s_waitcnt lgkmcnt(0)
	v_add_f32_e32 v64, v227, v64
	v_cndmask_b32_e32 v66, v206, v66, vcc
	v_lshlrev_b32_e32 v66, 2, v66
	ds_bpermute_b32 v68, v66, v64
	v_cmp_lt_i32_e32 vcc, v69, v67
	s_waitcnt lgkmcnt(0)
	v_add_f32_e32 v68, v64, v68
	v_cndmask_b32_e32 v64, v206, v69, vcc
	v_lshlrev_b32_e32 v67, 2, v64
	ds_bpermute_b32 v69, v67, v68
	v_cmp_eq_u32_e32 vcc, 0, v208
	v_lshl_add_u32 v64, v209, 2, 16
	s_and_saveexec_b64 s[14:15], vcc
	s_cbranch_execz .LBB0_66
	s_waitcnt lgkmcnt(0)
	v_add_f32_e32 v68, v68, v69
	v_fmamk_f32 v68, v68, 0x3a800000, v207
	v_mul_f32_e32 v69, 0x4b800000, v68
	v_cmp_gt_f32_e64 s[0:1], s21, v68
	s_nop 1
	v_cndmask_b32_e64 v68, v68, v69, s[0:1]
	v_rsq_f32_e32 v68, v68
	s_nop 0
	v_mul_f32_e32 v69, 0x45800000, v68
	v_cndmask_b32_e64 v68, v68, v69, s[0:1]
	v_add_u32_e32 v69, 0x12000, v64
	ds_write_b32 v69, v68
